# grid barrier: XCD leader no longer bumps the per-XCD generation word nobody polls (one atomic round trip less before it leaves the barrier)
# speedup vs baseline: 1.0209x; 1.0006x over previous
.LBB0_84:
	s_or_b64 exec, exec, s[6:7]
	s_mov_b64 s[6:7], exec
	v_mbcnt_lo_u32_b32 v2, s6, 0
	v_mbcnt_hi_u32_b32 v2, s7, v2
	s_mov_b32 s11, 0
	v_cmp_eq_u32_e32 vcc, 0, v2
	s_waitcnt vmcnt(0)
	buffer_inv sc1
	s_and_saveexec_b64 s[8:9], vcc
	s_cbranch_execz .LBB0_86
	s_add_i32 s10, s3, 0x900
	s_lshl_b64 s[10:11], s[10:11], 2
	s_add_u32 s4, s4, s10
	s_addc_u32 s5, s5, s11
	s_bcnt1_i32_b64 s3, s[6:7]
	v_mov_b32_e32 v2, 0
	v_mov_b32_e32 v3, s3
	s_nop 0

.LBB0_261:
	s_or_b64 exec, exec, s[8:9]
	s_mov_b64 s[8:9], exec
	v_mbcnt_lo_u32_b32 v2, s8, 0
	v_mbcnt_hi_u32_b32 v2, s9, v2
	s_mov_b32 s27, 0
	v_cmp_eq_u32_e32 vcc, 0, v2
	s_waitcnt vmcnt(0)
	buffer_inv sc1
	s_and_saveexec_b64 s[24:25], vcc
	s_cbranch_execz .LBB0_263
	s_add_i32 s26, s12, 0x900
	s_lshl_b64 s[12:13], s[26:27], 2
	s_add_u32 s6, s6, s12
	s_addc_u32 s7, s7, s13
	s_bcnt1_i32_b64 s8, s[8:9]
	v_mov_b32_e32 v2, 0
	v_mov_b32_e32 v3, s8
	s_nop 0

.LBB0_379:
	s_or_b64 exec, exec, s[6:7]
	s_mov_b64 s[6:7], exec
	v_mbcnt_lo_u32_b32 v1, s6, 0
	v_mbcnt_hi_u32_b32 v1, s7, v1
	s_mov_b32 s11, 0
	v_cmp_eq_u32_e32 vcc, 0, v1
	s_waitcnt vmcnt(0)
	buffer_inv sc1
	s_and_saveexec_b64 s[8:9], vcc
	s_cbranch_execz .LBB0_381
	s_add_i32 s10, s12, 0x900
	s_lshl_b64 s[10:11], s[10:11], 2
	s_add_u32 s4, s4, s10
	s_addc_u32 s5, s5, s11
	s_bcnt1_i32_b64 s6, s[6:7]
	v_mov_b32_e32 v1, 0
	v_mov_b32_e32 v2, s6
	s_nop 0

.LBB0_751:
	s_or_b64 exec, exec, s[8:9]
	s_mov_b64 s[8:9], exec
	v_mbcnt_lo_u32_b32 v1, s8, 0
	v_mbcnt_hi_u32_b32 v1, s9, v1
	v_cmp_eq_u32_e32 vcc, 0, v1
	s_waitcnt vmcnt(0)
	buffer_inv sc1
	s_and_saveexec_b64 s[36:37], vcc
	s_cbranch_execz .LBB0_753
	s_add_i32 s26, s12, 0x900
	s_lshl_b64 s[12:13], s[26:27], 2
	s_add_u32 s6, s6, s12
	s_addc_u32 s7, s7, s13
	s_bcnt1_i32_b64 s8, s[8:9]
	v_mov_b32_e32 v1, s8
	s_nop 0

.LBB0_806:
	s_or_b64 exec, exec, s[36:37]
	s_mov_b64 s[36:37], exec
	v_mbcnt_lo_u32_b32 v3, s36, 0
	v_mbcnt_hi_u32_b32 v3, s37, v3
	v_cmp_eq_u32_e32 vcc, 0, v3
	s_waitcnt vmcnt(0)
	buffer_inv sc1
	s_and_saveexec_b64 s[38:39], vcc
	s_cbranch_execz .LBB0_808
	s_add_i32 s26, s12, 0x900
	s_lshl_b64 s[12:13], s[26:27], 2
	s_add_u32 s12, s70, s12
	s_addc_u32 s13, s71, s13
	s_bcnt1_i32_b64 s14, s[36:37]
	v_mov_b32_e32 v3, s14
	s_nop 0

.LBB0_927:
	s_or_b64 exec, exec, s[6:7]
	s_mov_b64 s[6:7], exec
	v_mbcnt_lo_u32_b32 v1, s6, 0
	v_mbcnt_hi_u32_b32 v1, s7, v1
	v_cmp_eq_u32_e32 vcc, 0, v1
	s_waitcnt vmcnt(0)
	buffer_inv sc1
	s_and_saveexec_b64 s[8:9], vcc
	s_cbranch_execz .LBB0_518
	s_add_i32 s26, s12, 0x900
	s_lshl_b64 s[10:11], s[26:27], 2
	s_add_u32 s4, s4, s10
	s_addc_u32 s5, s5, s11
	s_bcnt1_i32_b64 s6, s[6:7]
	v_mov_b32_e32 v1, s6
	s_nop 0
	s_branch .LBB0_518
